# moe_down GEMM mainloop also converted to v_mfma_f32_16x16x32_bf16 ring schedule (proj, merge, moe_up, moe_down now converted)
# speedup vs baseline: 1.0395x; 1.0032x over previous
.LBB0_803:
	s_lshl_b32 s24, s31, 3
	v_readlane_b32 s25, v254, 21
	s_or_b32 s26, s24, s25
	s_cmp_lt_i32 s26, s28
	v_readlane_b32 s38, v254, 14
	s_cselect_b64 s[24:25], -1, 0
	v_readlane_b32 s39, v254, 15
	s_lshl_b32 s26, s26, 3
	v_readlane_b32 s27, v254, 22
	s_and_b64 s[24:25], s[38:39], s[24:25]
	s_add_i32 s40, s26, s27
	s_cmp_lt_i32 s40, s20
	s_cselect_b64 s[26:27], -1, 0
	s_and_b64 s[38:39], s[24:25], exec
	v_readlane_b32 s38, v253, 15
	s_cselect_b32 s37, s40, s37
	s_cselect_b32 s36, s38, s36
	s_and_b64 s[24:25], s[24:25], s[26:27]
	s_andn2_b64 vcc, exec, s[24:25]
	s_cbranch_vccnz .LBB0_802
	ds_read2_b32 v[0:1], v224 offset1:1
	ds_read2_b32 v[2:3], v225 offset1:1
	ds_read2_b32 v[4:5], v226 offset1:1
	ds_read2_b32 v[6:7], v227 offset1:1
	s_lshl_b32 s24, s36, 8
	s_waitcnt lgkmcnt(3)
	v_cmp_ge_i32_e32 vcc, s37, v0
	v_cmp_lt_i32_e64 s[40:41], s37, v1
	v_mov_b32_e32 v20, v195
	v_cndmask_b32_e64 v0, 0, 1, vcc
	v_cndmask_b32_e64 v0, 2, v0, s[40:41]
	s_waitcnt lgkmcnt(2)
	v_cmp_lt_i32_e32 vcc, s37, v2
	v_mov_b32_e32 v9, v193
	v_mov_b32_e32 v11, v193
	v_cndmask_b32_e32 v0, 3, v0, vcc
	v_cmp_lt_i32_e32 vcc, s37, v3
	v_mov_b32_e32 v13, v193
	s_mov_b64 s[60:61], 0x100
	v_cndmask_b32_e32 v0, 4, v0, vcc
	s_waitcnt lgkmcnt(1)
	v_cmp_lt_i32_e32 vcc, s37, v4
	s_nop 1
	v_cndmask_b32_e32 v0, 5, v0, vcc
	v_cmp_lt_i32_e32 vcc, s37, v5
	s_nop 1
	v_cndmask_b32_e32 v0, 6, v0, vcc
	s_waitcnt lgkmcnt(0)
	v_cmp_lt_i32_e32 vcc, s37, v6
	s_nop 1
	v_cndmask_b32_e32 v2, 7, v0, vcc
	ds_read2_b32 v[0:1], v228 offset1:1
	v_cmp_lt_i32_e32 vcc, s37, v7
	s_nop 1
	v_cndmask_b32_e32 v6, 8, v2, vcc
	ds_read2_b32 v[2:3], v229 offset1:1
	ds_read2_b32 v[4:5], v230 offset1:1
	ds_read_b32 v7, v231
	s_waitcnt lgkmcnt(3)
	v_cmp_lt_i32_e32 vcc, s37, v0
	s_nop 1
	v_cndmask_b32_e32 v0, 9, v6, vcc
	v_cmp_lt_i32_e32 vcc, s37, v1
	s_nop 1
	v_cndmask_b32_e32 v0, 10, v0, vcc
	s_waitcnt lgkmcnt(2)
	v_cmp_lt_i32_e32 vcc, s37, v2
	s_nop 1
	v_cndmask_b32_e32 v0, 11, v0, vcc
	v_cmp_lt_i32_e32 vcc, s37, v3
	s_nop 1
	v_cndmask_b32_e32 v0, 12, v0, vcc
	s_waitcnt lgkmcnt(1)
	v_cmp_lt_i32_e32 vcc, s37, v4
	s_nop 1
	v_cndmask_b32_e32 v0, 13, v0, vcc
	v_cmp_lt_i32_e32 vcc, s37, v5
	v_add_lshl_u32 v5, s24, v152, 9
	v_add_u32_e32 v4, v5, v155
	v_cndmask_b32_e32 v0, 14, v0, vcc
	s_waitcnt lgkmcnt(0)
	v_cmp_lt_i32_e32 vcc, s37, v7
	v_add_u32_e32 v8, v5, v156
	v_add_u32_e32 v12, v5, v157
	v_cndmask_b32_e32 v160, 15, v0, vcc
	v_lshlrev_b32_e32 v0, 2, v160
	v_add_u32_e32 v0, 0x24000, v0
	ds_read_b32 v159, v0 offset:128
	ds_read2_b32 v[132:133], v0 offset1:16
	v_add_u32_e32 v0, s29, v160
	v_ashrrev_i32_e32 v1, 31, v0
	v_lshlrev_b64 v[0:1], 20, v[0:1]
	s_waitcnt lgkmcnt(1)
	v_sub_u32_e32 v2, s37, v159
	v_lshl_add_u64 v[134:135], s[4:5], 0, v[0:1]
	v_lshl_add_u32 v1, v2, 8, v152
	s_waitcnt lgkmcnt(0)
	v_add_u32_e32 v3, -1, v132
	v_min_i32_e32 v0, v1, v3
	v_add_u32_e32 v2, 64, v1
	v_add_u32_e32 v6, 0x80, v1
	v_add_u32_e32 v1, 0xc0, v1
	v_add_u32_e32 v0, v0, v133
	v_min_i32_e32 v1, v1, v3
	v_lshl_or_b32 v192, v0, 9, v153
	v_min_i32_e32 v2, v2, v3
	v_add_u32_e32 v1, v1, v133
	v_or_b32_e32 v0, v5, v153
	v_readfirstlane_b32 s25, v20
	v_add_u32_e32 v2, v2, v133
	v_lshl_or_b32 v10, v1, 9, v153
	s_lshl_b32 s25, s25, 4
	v_lshlrev_b64 v[136:137], 1, v[192:193]
	v_mov_b32_e32 v1, v193
	v_lshl_or_b32 v2, v2, 9, v153
	v_min_i32_e32 v6, v6, v3
	s_and_b32 s44, s25, 0xfffffc00
	v_lshl_add_u64 v[14:15], s[2:3], 0, v[136:137]
	s_mov_b32 s25, m0
	s_mov_b32 m0, s44
	s_nop 0
	global_load_lds_dwordx4 v[14:15], off
	s_mov_b32 m0, s25
	v_lshlrev_b64 v[138:139], 1, v[0:1]
	v_mov_b32_e32 v3, v193
	v_add_u32_e32 v6, v6, v133
	s_add_i32 s43, s44, 0x8000
	v_lshl_add_u64 v[0:1], v[134:135], 0, v[138:139]
	s_mov_b32 s25, m0
	s_mov_b32 m0, s43
	s_nop 0
	global_load_lds_dwordx4 v[0:1], off
	s_mov_b32 m0, s25
	v_lshlrev_b64 v[140:141], 1, v[2:3]
	v_mov_b32_e32 v5, v193
	v_lshl_or_b32 v6, v6, 9, v153
	v_lshl_add_u64 v[0:1], s[2:3], 0, v[140:141]
	s_add_i32 s45, s44, 0x2000
	s_mov_b32 s25, m0
	s_mov_b32 m0, s45
	s_nop 0
	global_load_lds_dwordx4 v[0:1], off
	s_mov_b32 m0, s25
	v_lshlrev_b64 v[142:143], 1, v[4:5]
	v_mov_b32_e32 v7, v193
	v_lshl_add_u64 v[0:1], v[134:135], 0, v[142:143]
	s_add_i32 s46, s44, 0xa000
	s_mov_b32 s25, m0
	s_mov_b32 m0, s46
	s_nop 0
	global_load_lds_dwordx4 v[0:1], off
	s_mov_b32 m0, s25
	v_lshlrev_b64 v[144:145], 1, v[6:7]
	v_lshl_add_u64 v[0:1], s[2:3], 0, v[144:145]
	s_add_i32 s47, s44, 0x4000
	s_mov_b32 s25, m0
	s_mov_b32 m0, s47
	s_nop 0
	global_load_lds_dwordx4 v[0:1], off
	s_mov_b32 m0, s25
	v_lshlrev_b64 v[146:147], 1, v[8:9]
	v_lshl_add_u64 v[0:1], v[134:135], 0, v[146:147]
	s_add_i32 s48, s44, 0xc000
	s_mov_b32 s25, m0
	s_mov_b32 m0, s48
	s_nop 0
	global_load_lds_dwordx4 v[0:1], off
	s_mov_b32 m0, s25
	v_lshlrev_b64 v[148:149], 1, v[10:11]
	v_lshl_add_u64 v[0:1], s[2:3], 0, v[148:149]
	s_add_i32 s49, s44, 0x6000
	s_mov_b32 s25, m0
	s_mov_b32 m0, s49
	s_nop 0
	global_load_lds_dwordx4 v[0:1], off
	s_mov_b32 m0, s25
	v_lshlrev_b64 v[150:151], 1, v[12:13]
	v_lshl_add_u64 v[0:1], v[134:135], 0, v[150:151]
	s_add_i32 s50, s44, 0xe000
	s_mov_b32 s25, m0
	s_mov_b32 m0, s50
	s_nop 0
	global_load_lds_dwordx4 v[0:1], off
	s_mov_b32 m0, s25
	v_and_b32_e32 v17, 31, v20
	v_lshrrev_b32_e32 v0, 1, v20
	s_mov_b32 s25, 0x1ffff80
	v_lshrrev_b32_e32 v16, 5, v20
	v_bfe_u32 v1, v20, 1, 3
	v_and_or_b32 v0, v0, s25, v17
	v_lshlrev_b32_e32 v163, 7, v0
	v_bitop3_b32 v0, v16, v1, 1 bitop3:0x6c
	v_lshlrev_b32_e32 v164, 4, v0
	v_lshl_add_u64 v[0:1], s[6:7], 0, v[136:137]
	s_waitcnt vmcnt(0)
	s_barrier
	s_mov_b32 s39, m0
	s_mov_b32 s40, s2
	s_mov_b32 s41, s3
	v_readfirstlane_b32 s42, v134
	v_readfirstlane_b32 s43, v135
	v_and_b32_e32 v4, 15, v195
	v_lshrrev_b32_e32 v5, 8, v195
	v_lshl_add_u32 v5, v5, 7, v4
	v_lshlrev_b32_e32 v5, 7, v5
	v_bfe_u32 v6, v195, 4, 2
	v_bfe_u32 v7, v195, 1, 3
	v_xor_b32_e32 v6, v6, v7
	v_lshlrev_b32_e32 v6, 4, v6
	v_or_b32_e32 v161, v5, v6
	v_xor_b32_e32 v186, 64, v161
	v_bfe_u32 v7, v195, 6, 2
	v_lshl_add_u32 v7, v7, 6, v4
	v_lshlrev_b32_e32 v7, 7, v7
	v_or_b32_e32 v187, v7, v6
	v_xor_b32_e32 v248, 64, v187
	s_add_u32 s40, s40, 0x80
	s_addc_u32 s41, s41, 0
	s_add_u32 s42, s42, 0x80
	s_addc_u32 s43, s43, 0
	ds_read_b128 v[178:181], v187 offset:32768
	ds_read_b128 v[182:185], v187 offset:34816
	ds_read_b128 v[196:199], v187 offset:36864
	ds_read_b128 v[200:203], v187 offset:38912
	ds_read_b128 v[162:165], v161
	ds_read_b128 v[166:169], v161 offset:2048
	ds_read_b128 v[170:173], v161 offset:4096
	s_add_u32 m0, s44, 0x10000
	s_nop 0
	global_load_lds_dwordx4 v136, s[40:41]
	s_add_u32 m0, s44, 0x18000
	s_nop 0
	global_load_lds_dwordx4 v138, s[42:43]
	s_add_u32 m0, s44, 0x12000
	s_nop 0
	global_load_lds_dwordx4 v140, s[40:41]
	s_add_u32 m0, s44, 0x1a000
	s_nop 0
	global_load_lds_dwordx4 v142, s[42:43]
	s_add_u32 m0, s44, 0x14000
	s_nop 0
	global_load_lds_dwordx4 v144, s[40:41]
	s_add_u32 m0, s44, 0x1c000
	s_nop 0
	global_load_lds_dwordx4 v146, s[42:43]
	s_add_u32 m0, s44, 0x16000
	s_nop 0
	global_load_lds_dwordx4 v148, s[40:41]
	s_add_u32 m0, s44, 0x1e000
	s_nop 0
	global_load_lds_dwordx4 v150, s[42:43]
	s_add_u32 s40, s40, 0x80
	s_addc_u32 s41, s41, 0
	s_add_u32 s42, s42, 0x80
	s_addc_u32 s43, s43, 0
	s_waitcnt lgkmcnt(2)
	v_mfma_f32_16x16x32_bf16 v[0:3], v[162:165], v[178:181], 0
	ds_read_b128 v[174:177], v161 offset:6144
	v_mfma_f32_16x16x32_bf16 v[4:7], v[162:165], v[182:185], 0
	ds_read_b128 v[212:215], v248 offset:32768
	v_mfma_f32_16x16x32_bf16 v[8:11], v[162:165], v[196:199], 0
	v_mfma_f32_16x16x32_bf16 v[12:15], v[162:165], v[200:203], 0
	s_waitcnt lgkmcnt(3)
	v_mfma_f32_16x16x32_bf16 v[16:19], v[166:169], v[178:181], 0
	ds_read_b128 v[162:165], v161 offset:8192
	v_mfma_f32_16x16x32_bf16 v[20:23], v[166:169], v[182:185], 0
	ds_read_b128 v[216:219], v248 offset:34816
	v_mfma_f32_16x16x32_bf16 v[24:27], v[166:169], v[196:199], 0
	v_mfma_f32_16x16x32_bf16 v[28:31], v[166:169], v[200:203], 0
	s_waitcnt lgkmcnt(4)
	v_mfma_f32_16x16x32_bf16 v[32:35], v[170:173], v[178:181], 0
	ds_read_b128 v[166:169], v161 offset:10240
	v_mfma_f32_16x16x32_bf16 v[36:39], v[170:173], v[182:185], 0
	ds_read_b128 v[240:243], v248 offset:36864
	v_mfma_f32_16x16x32_bf16 v[40:43], v[170:173], v[196:199], 0
	v_mfma_f32_16x16x32_bf16 v[44:47], v[170:173], v[200:203], 0
	s_waitcnt lgkmcnt(5)
	v_mfma_f32_16x16x32_bf16 v[48:51], v[174:177], v[178:181], 0
	ds_read_b128 v[170:173], v161 offset:12288
	v_mfma_f32_16x16x32_bf16 v[52:55], v[174:177], v[182:185], 0
	ds_read_b128 v[244:247], v248 offset:38912
	v_mfma_f32_16x16x32_bf16 v[56:59], v[174:177], v[196:199], 0
	v_mfma_f32_16x16x32_bf16 v[60:63], v[174:177], v[200:203], 0
	s_waitcnt lgkmcnt(5)
	v_mfma_f32_16x16x32_bf16 v[64:67], v[162:165], v[178:181], 0
	ds_read_b128 v[174:177], v161 offset:14336
	v_mfma_f32_16x16x32_bf16 v[68:71], v[162:165], v[182:185], 0
	v_mfma_f32_16x16x32_bf16 v[72:75], v[162:165], v[196:199], 0
	v_mfma_f32_16x16x32_bf16 v[76:79], v[162:165], v[200:203], 0
	s_waitcnt lgkmcnt(4)
	v_mfma_f32_16x16x32_bf16 v[80:83], v[166:169], v[178:181], 0
	ds_read_b128 v[162:165], v186
	v_mfma_f32_16x16x32_bf16 v[84:87], v[166:169], v[182:185], 0
	v_mfma_f32_16x16x32_bf16 v[88:91], v[166:169], v[196:199], 0
	v_mfma_f32_16x16x32_bf16 v[92:95], v[166:169], v[200:203], 0
	s_waitcnt lgkmcnt(3)
	v_mfma_f32_16x16x32_bf16 v[96:99], v[170:173], v[178:181], 0
	ds_read_b128 v[166:169], v186 offset:2048
	v_mfma_f32_16x16x32_bf16 v[100:103], v[170:173], v[182:185], 0
	v_mfma_f32_16x16x32_bf16 v[104:107], v[170:173], v[196:199], 0
	v_mfma_f32_16x16x32_bf16 v[108:111], v[170:173], v[200:203], 0
	s_waitcnt lgkmcnt(2)
	v_mfma_f32_16x16x32_bf16 v[112:115], v[174:177], v[178:181], 0
	ds_read_b128 v[170:173], v186 offset:4096
	v_mfma_f32_16x16x32_bf16 v[116:119], v[174:177], v[182:185], 0
	v_mfma_f32_16x16x32_bf16 v[120:123], v[174:177], v[196:199], 0
	v_mfma_f32_16x16x32_bf16 v[124:127], v[174:177], v[200:203], 0
	s_waitcnt lgkmcnt(2)
	v_mfma_f32_16x16x32_bf16 v[0:3], v[162:165], v[212:215], v[0:3]
	ds_read_b128 v[174:177], v186 offset:6144
	v_mfma_f32_16x16x32_bf16 v[4:7], v[162:165], v[216:219], v[4:7]
	v_mfma_f32_16x16x32_bf16 v[8:11], v[162:165], v[240:243], v[8:11]
	v_mfma_f32_16x16x32_bf16 v[12:15], v[162:165], v[244:247], v[12:15]
	s_waitcnt lgkmcnt(2)
	v_mfma_f32_16x16x32_bf16 v[16:19], v[166:169], v[212:215], v[16:19]
	ds_read_b128 v[162:165], v186 offset:8192
	v_mfma_f32_16x16x32_bf16 v[20:23], v[166:169], v[216:219], v[20:23]
	v_mfma_f32_16x16x32_bf16 v[24:27], v[166:169], v[240:243], v[24:27]
	v_mfma_f32_16x16x32_bf16 v[28:31], v[166:169], v[244:247], v[28:31]
	s_waitcnt lgkmcnt(2)
	v_mfma_f32_16x16x32_bf16 v[32:35], v[170:173], v[212:215], v[32:35]
	ds_read_b128 v[166:169], v186 offset:10240
	v_mfma_f32_16x16x32_bf16 v[36:39], v[170:173], v[216:219], v[36:39]
	v_mfma_f32_16x16x32_bf16 v[40:43], v[170:173], v[240:243], v[40:43]
	v_mfma_f32_16x16x32_bf16 v[44:47], v[170:173], v[244:247], v[44:47]
	s_waitcnt lgkmcnt(2)
	v_mfma_f32_16x16x32_bf16 v[48:51], v[174:177], v[212:215], v[48:51]
	ds_read_b128 v[170:173], v186 offset:12288
	v_mfma_f32_16x16x32_bf16 v[52:55], v[174:177], v[216:219], v[52:55]
	v_mfma_f32_16x16x32_bf16 v[56:59], v[174:177], v[240:243], v[56:59]
	v_mfma_f32_16x16x32_bf16 v[60:63], v[174:177], v[244:247], v[60:63]
	s_waitcnt lgkmcnt(2)
	v_mfma_f32_16x16x32_bf16 v[64:67], v[162:165], v[212:215], v[64:67]
	ds_read_b128 v[174:177], v186 offset:14336
	v_mfma_f32_16x16x32_bf16 v[68:71], v[162:165], v[216:219], v[68:71]
	v_mfma_f32_16x16x32_bf16 v[72:75], v[162:165], v[240:243], v[72:75]
	v_mfma_f32_16x16x32_bf16 v[76:79], v[162:165], v[244:247], v[76:79]
	s_waitcnt lgkmcnt(2)
	v_mfma_f32_16x16x32_bf16 v[80:83], v[166:169], v[212:215], v[80:83]
	v_mfma_f32_16x16x32_bf16 v[84:87], v[166:169], v[216:219], v[84:87]
	v_mfma_f32_16x16x32_bf16 v[88:91], v[166:169], v[240:243], v[88:91]
	v_mfma_f32_16x16x32_bf16 v[92:95], v[166:169], v[244:247], v[92:95]
	s_waitcnt lgkmcnt(0)
	s_waitcnt vmcnt(0)
	s_barrier
	v_xor_b32_e32 v161, 0x10000, v161
	v_xor_b32_e32 v186, 0x10000, v186
	v_xor_b32_e32 v187, 0x10000, v187
	v_xor_b32_e32 v248, 0x10000, v248
	v_mfma_f32_16x16x32_bf16 v[96:99], v[170:173], v[212:215], v[96:99]
	ds_read_b128 v[162:165], v161
	ds_read_b128 v[166:169], v161 offset:2048
	s_mov_b32 m0, s44
	v_mfma_f32_16x16x32_bf16 v[100:103], v[170:173], v[216:219], v[100:103]
	global_load_lds_dwordx4 v136, s[40:41]
	v_mfma_f32_16x16x32_bf16 v[104:107], v[170:173], v[240:243], v[104:107]
	ds_read_b128 v[178:181], v187 offset:32768
	ds_read_b128 v[182:185], v187 offset:34816
	s_add_u32 m0, s44, 0x8000
	v_mfma_f32_16x16x32_bf16 v[108:111], v[170:173], v[244:247], v[108:111]
	global_load_lds_dwordx4 v138, s[42:43]
	v_mfma_f32_16x16x32_bf16 v[112:115], v[174:177], v[212:215], v[112:115]
	ds_read_b128 v[170:173], v161 offset:4096
	s_add_u32 m0, s44, 0x2000
	v_mfma_f32_16x16x32_bf16 v[116:119], v[174:177], v[216:219], v[116:119]
	global_load_lds_dwordx4 v140, s[40:41]
	ds_read_b128 v[196:199], v187 offset:36864
	ds_read_b128 v[200:203], v187 offset:38912
	v_mfma_f32_16x16x32_bf16 v[120:123], v[174:177], v[240:243], v[120:123]
	s_add_u32 m0, s44, 0xa000
	v_mfma_f32_16x16x32_bf16 v[124:127], v[174:177], v[244:247], v[124:127]
	global_load_lds_dwordx4 v142, s[42:43]
	s_waitcnt lgkmcnt(4)
	v_mfma_f32_16x16x32_bf16 v[0:3], v[162:165], v[178:181], v[0:3]
	ds_read_b128 v[174:177], v161 offset:6144
	s_waitcnt lgkmcnt(4)
	v_mfma_f32_16x16x32_bf16 v[4:7], v[162:165], v[182:185], v[4:7]
	ds_read_b128 v[212:215], v248 offset:32768
	s_waitcnt lgkmcnt(3)
	v_mfma_f32_16x16x32_bf16 v[8:11], v[162:165], v[196:199], v[8:11]
	s_waitcnt lgkmcnt(2)
	v_mfma_f32_16x16x32_bf16 v[12:15], v[162:165], v[200:203], v[12:15]
	v_mfma_f32_16x16x32_bf16 v[16:19], v[166:169], v[178:181], v[16:19]
	ds_read_b128 v[162:165], v161 offset:8192
	v_mfma_f32_16x16x32_bf16 v[20:23], v[166:169], v[182:185], v[20:23]
	ds_read_b128 v[216:219], v248 offset:34816
	v_mfma_f32_16x16x32_bf16 v[24:27], v[166:169], v[196:199], v[24:27]
	v_mfma_f32_16x16x32_bf16 v[28:31], v[166:169], v[200:203], v[28:31]
	v_mfma_f32_16x16x32_bf16 v[32:35], v[170:173], v[178:181], v[32:35]
	ds_read_b128 v[166:169], v161 offset:10240
	v_mfma_f32_16x16x32_bf16 v[36:39], v[170:173], v[182:185], v[36:39]
	ds_read_b128 v[240:243], v248 offset:36864
	v_mfma_f32_16x16x32_bf16 v[40:43], v[170:173], v[196:199], v[40:43]
	s_add_u32 m0, s44, 0x4000
	v_mfma_f32_16x16x32_bf16 v[44:47], v[170:173], v[200:203], v[44:47]
	global_load_lds_dwordx4 v144, s[40:41]
	s_waitcnt lgkmcnt(5)
	v_mfma_f32_16x16x32_bf16 v[48:51], v[174:177], v[178:181], v[48:51]
	ds_read_b128 v[170:173], v161 offset:12288
	v_mfma_f32_16x16x32_bf16 v[52:55], v[174:177], v[182:185], v[52:55]
	ds_read_b128 v[244:247], v248 offset:38912
	v_mfma_f32_16x16x32_bf16 v[56:59], v[174:177], v[196:199], v[56:59]
	s_add_u32 m0, s44, 0xc000
	v_mfma_f32_16x16x32_bf16 v[60:63], v[174:177], v[200:203], v[60:63]
	global_load_lds_dwordx4 v146, s[42:43]
	s_waitcnt lgkmcnt(5)
	v_mfma_f32_16x16x32_bf16 v[64:67], v[162:165], v[178:181], v[64:67]
	ds_read_b128 v[174:177], v161 offset:14336
	v_mfma_f32_16x16x32_bf16 v[68:71], v[162:165], v[182:185], v[68:71]
	v_mfma_f32_16x16x32_bf16 v[72:75], v[162:165], v[196:199], v[72:75]
	s_add_u32 m0, s44, 0x6000
	v_mfma_f32_16x16x32_bf16 v[76:79], v[162:165], v[200:203], v[76:79]
	global_load_lds_dwordx4 v148, s[40:41]
	s_waitcnt lgkmcnt(4)
	v_mfma_f32_16x16x32_bf16 v[80:83], v[166:169], v[178:181], v[80:83]
	ds_read_b128 v[162:165], v186
	v_mfma_f32_16x16x32_bf16 v[84:87], v[166:169], v[182:185], v[84:87]
	v_mfma_f32_16x16x32_bf16 v[88:91], v[166:169], v[196:199], v[88:91]
	s_add_u32 m0, s44, 0xe000
	v_mfma_f32_16x16x32_bf16 v[92:95], v[166:169], v[200:203], v[92:95]
	global_load_lds_dwordx4 v150, s[42:43]
	s_add_u32 s40, s40, 0x80
	s_addc_u32 s41, s41, 0
	s_add_u32 s42, s42, 0x80
	s_addc_u32 s43, s43, 0
	s_waitcnt lgkmcnt(3)
	v_mfma_f32_16x16x32_bf16 v[96:99], v[170:173], v[178:181], v[96:99]
	ds_read_b128 v[166:169], v186 offset:2048
	v_mfma_f32_16x16x32_bf16 v[100:103], v[170:173], v[182:185], v[100:103]
	v_mfma_f32_16x16x32_bf16 v[104:107], v[170:173], v[196:199], v[104:107]
	v_mfma_f32_16x16x32_bf16 v[108:111], v[170:173], v[200:203], v[108:111]
	s_waitcnt lgkmcnt(2)
	v_mfma_f32_16x16x32_bf16 v[112:115], v[174:177], v[178:181], v[112:115]
	ds_read_b128 v[170:173], v186 offset:4096
	v_mfma_f32_16x16x32_bf16 v[116:119], v[174:177], v[182:185], v[116:119]
	v_mfma_f32_16x16x32_bf16 v[120:123], v[174:177], v[196:199], v[120:123]
	v_mfma_f32_16x16x32_bf16 v[124:127], v[174:177], v[200:203], v[124:127]
	s_waitcnt lgkmcnt(2)
	v_mfma_f32_16x16x32_bf16 v[0:3], v[162:165], v[212:215], v[0:3]
	ds_read_b128 v[174:177], v186 offset:6144
	v_mfma_f32_16x16x32_bf16 v[4:7], v[162:165], v[216:219], v[4:7]
	v_mfma_f32_16x16x32_bf16 v[8:11], v[162:165], v[240:243], v[8:11]
	v_mfma_f32_16x16x32_bf16 v[12:15], v[162:165], v[244:247], v[12:15]
	s_waitcnt lgkmcnt(2)
	v_mfma_f32_16x16x32_bf16 v[16:19], v[166:169], v[212:215], v[16:19]
	ds_read_b128 v[162:165], v186 offset:8192
	v_mfma_f32_16x16x32_bf16 v[20:23], v[166:169], v[216:219], v[20:23]
	v_mfma_f32_16x16x32_bf16 v[24:27], v[166:169], v[240:243], v[24:27]
	v_mfma_f32_16x16x32_bf16 v[28:31], v[166:169], v[244:247], v[28:31]
	s_waitcnt lgkmcnt(2)
	v_mfma_f32_16x16x32_bf16 v[32:35], v[170:173], v[212:215], v[32:35]
	ds_read_b128 v[166:169], v186 offset:10240
	v_mfma_f32_16x16x32_bf16 v[36:39], v[170:173], v[216:219], v[36:39]
	v_mfma_f32_16x16x32_bf16 v[40:43], v[170:173], v[240:243], v[40:43]
	v_mfma_f32_16x16x32_bf16 v[44:47], v[170:173], v[244:247], v[44:47]
	s_waitcnt lgkmcnt(2)
	v_mfma_f32_16x16x32_bf16 v[48:51], v[174:177], v[212:215], v[48:51]
	ds_read_b128 v[170:173], v186 offset:12288
	v_mfma_f32_16x16x32_bf16 v[52:55], v[174:177], v[216:219], v[52:55]
	v_mfma_f32_16x16x32_bf16 v[56:59], v[174:177], v[240:243], v[56:59]
	v_mfma_f32_16x16x32_bf16 v[60:63], v[174:177], v[244:247], v[60:63]
	s_waitcnt lgkmcnt(2)
	v_mfma_f32_16x16x32_bf16 v[64:67], v[162:165], v[212:215], v[64:67]
	ds_read_b128 v[174:177], v186 offset:14336
	v_mfma_f32_16x16x32_bf16 v[68:71], v[162:165], v[216:219], v[68:71]
	v_mfma_f32_16x16x32_bf16 v[72:75], v[162:165], v[240:243], v[72:75]
	v_mfma_f32_16x16x32_bf16 v[76:79], v[162:165], v[244:247], v[76:79]
	s_waitcnt lgkmcnt(2)
	v_mfma_f32_16x16x32_bf16 v[80:83], v[166:169], v[212:215], v[80:83]
	v_mfma_f32_16x16x32_bf16 v[84:87], v[166:169], v[216:219], v[84:87]
	v_mfma_f32_16x16x32_bf16 v[88:91], v[166:169], v[240:243], v[88:91]
	v_mfma_f32_16x16x32_bf16 v[92:95], v[166:169], v[244:247], v[92:95]
	s_waitcnt lgkmcnt(0)
	s_waitcnt vmcnt(0)
	s_barrier
	v_xor_b32_e32 v161, 0x10000, v161
	v_xor_b32_e32 v186, 0x10000, v186
	v_xor_b32_e32 v187, 0x10000, v187
	v_xor_b32_e32 v248, 0x10000, v248
	v_mfma_f32_16x16x32_bf16 v[96:99], v[170:173], v[212:215], v[96:99]
	ds_read_b128 v[162:165], v161
	ds_read_b128 v[166:169], v161 offset:2048
	s_add_u32 m0, s44, 0x10000
	v_mfma_f32_16x16x32_bf16 v[100:103], v[170:173], v[216:219], v[100:103]
	global_load_lds_dwordx4 v136, s[40:41]
	v_mfma_f32_16x16x32_bf16 v[104:107], v[170:173], v[240:243], v[104:107]
	ds_read_b128 v[178:181], v187 offset:32768
	ds_read_b128 v[182:185], v187 offset:34816
	s_add_u32 m0, s44, 0x18000
	v_mfma_f32_16x16x32_bf16 v[108:111], v[170:173], v[244:247], v[108:111]
	global_load_lds_dwordx4 v138, s[42:43]
	v_mfma_f32_16x16x32_bf16 v[112:115], v[174:177], v[212:215], v[112:115]
	ds_read_b128 v[170:173], v161 offset:4096
	s_add_u32 m0, s44, 0x12000
	v_mfma_f32_16x16x32_bf16 v[116:119], v[174:177], v[216:219], v[116:119]
	global_load_lds_dwordx4 v140, s[40:41]
	ds_read_b128 v[196:199], v187 offset:36864
	ds_read_b128 v[200:203], v187 offset:38912
	v_mfma_f32_16x16x32_bf16 v[120:123], v[174:177], v[240:243], v[120:123]
	s_add_u32 m0, s44, 0x1a000
	v_mfma_f32_16x16x32_bf16 v[124:127], v[174:177], v[244:247], v[124:127]
	global_load_lds_dwordx4 v142, s[42:43]
	s_waitcnt lgkmcnt(4)
	v_mfma_f32_16x16x32_bf16 v[0:3], v[162:165], v[178:181], v[0:3]
	ds_read_b128 v[174:177], v161 offset:6144
	s_waitcnt lgkmcnt(4)
	v_mfma_f32_16x16x32_bf16 v[4:7], v[162:165], v[182:185], v[4:7]
	ds_read_b128 v[212:215], v248 offset:32768
	s_waitcnt lgkmcnt(3)
	v_mfma_f32_16x16x32_bf16 v[8:11], v[162:165], v[196:199], v[8:11]
	s_waitcnt lgkmcnt(2)
	v_mfma_f32_16x16x32_bf16 v[12:15], v[162:165], v[200:203], v[12:15]
	v_mfma_f32_16x16x32_bf16 v[16:19], v[166:169], v[178:181], v[16:19]
	ds_read_b128 v[162:165], v161 offset:8192
	v_mfma_f32_16x16x32_bf16 v[20:23], v[166:169], v[182:185], v[20:23]
	ds_read_b128 v[216:219], v248 offset:34816
	v_mfma_f32_16x16x32_bf16 v[24:27], v[166:169], v[196:199], v[24:27]
	v_mfma_f32_16x16x32_bf16 v[28:31], v[166:169], v[200:203], v[28:31]
	v_mfma_f32_16x16x32_bf16 v[32:35], v[170:173], v[178:181], v[32:35]
	ds_read_b128 v[166:169], v161 offset:10240
	v_mfma_f32_16x16x32_bf16 v[36:39], v[170:173], v[182:185], v[36:39]
	ds_read_b128 v[240:243], v248 offset:36864
	v_mfma_f32_16x16x32_bf16 v[40:43], v[170:173], v[196:199], v[40:43]
	s_add_u32 m0, s44, 0x14000
	v_mfma_f32_16x16x32_bf16 v[44:47], v[170:173], v[200:203], v[44:47]
	global_load_lds_dwordx4 v144, s[40:41]
	s_waitcnt lgkmcnt(5)
	v_mfma_f32_16x16x32_bf16 v[48:51], v[174:177], v[178:181], v[48:51]
	ds_read_b128 v[170:173], v161 offset:12288
	v_mfma_f32_16x16x32_bf16 v[52:55], v[174:177], v[182:185], v[52:55]
	ds_read_b128 v[244:247], v248 offset:38912
	v_mfma_f32_16x16x32_bf16 v[56:59], v[174:177], v[196:199], v[56:59]
	s_add_u32 m0, s44, 0x1c000
	v_mfma_f32_16x16x32_bf16 v[60:63], v[174:177], v[200:203], v[60:63]
	global_load_lds_dwordx4 v146, s[42:43]
	s_waitcnt lgkmcnt(5)
	v_mfma_f32_16x16x32_bf16 v[64:67], v[162:165], v[178:181], v[64:67]
	ds_read_b128 v[174:177], v161 offset:14336
	v_mfma_f32_16x16x32_bf16 v[68:71], v[162:165], v[182:185], v[68:71]
	v_mfma_f32_16x16x32_bf16 v[72:75], v[162:165], v[196:199], v[72:75]
	s_add_u32 m0, s44, 0x16000
	v_mfma_f32_16x16x32_bf16 v[76:79], v[162:165], v[200:203], v[76:79]
	global_load_lds_dwordx4 v148, s[40:41]
	s_waitcnt lgkmcnt(4)
	v_mfma_f32_16x16x32_bf16 v[80:83], v[166:169], v[178:181], v[80:83]
	ds_read_b128 v[162:165], v186
	v_mfma_f32_16x16x32_bf16 v[84:87], v[166:169], v[182:185], v[84:87]
	v_mfma_f32_16x16x32_bf16 v[88:91], v[166:169], v[196:199], v[88:91]
	s_add_u32 m0, s44, 0x1e000
	v_mfma_f32_16x16x32_bf16 v[92:95], v[166:169], v[200:203], v[92:95]
	global_load_lds_dwordx4 v150, s[42:43]
	s_add_u32 s40, s40, 0x80
	s_addc_u32 s41, s41, 0
	s_add_u32 s42, s42, 0x80
	s_addc_u32 s43, s43, 0
	s_waitcnt lgkmcnt(3)
	v_mfma_f32_16x16x32_bf16 v[96:99], v[170:173], v[178:181], v[96:99]
	ds_read_b128 v[166:169], v186 offset:2048
	v_mfma_f32_16x16x32_bf16 v[100:103], v[170:173], v[182:185], v[100:103]
	v_mfma_f32_16x16x32_bf16 v[104:107], v[170:173], v[196:199], v[104:107]
	v_mfma_f32_16x16x32_bf16 v[108:111], v[170:173], v[200:203], v[108:111]
	s_waitcnt lgkmcnt(2)
	v_mfma_f32_16x16x32_bf16 v[112:115], v[174:177], v[178:181], v[112:115]
	ds_read_b128 v[170:173], v186 offset:4096
	v_mfma_f32_16x16x32_bf16 v[116:119], v[174:177], v[182:185], v[116:119]
	v_mfma_f32_16x16x32_bf16 v[120:123], v[174:177], v[196:199], v[120:123]
	v_mfma_f32_16x16x32_bf16 v[124:127], v[174:177], v[200:203], v[124:127]
	s_waitcnt lgkmcnt(2)
	v_mfma_f32_16x16x32_bf16 v[0:3], v[162:165], v[212:215], v[0:3]
	ds_read_b128 v[174:177], v186 offset:6144
	v_mfma_f32_16x16x32_bf16 v[4:7], v[162:165], v[216:219], v[4:7]
	v_mfma_f32_16x16x32_bf16 v[8:11], v[162:165], v[240:243], v[8:11]
	v_mfma_f32_16x16x32_bf16 v[12:15], v[162:165], v[244:247], v[12:15]
	s_waitcnt lgkmcnt(2)
	v_mfma_f32_16x16x32_bf16 v[16:19], v[166:169], v[212:215], v[16:19]
	ds_read_b128 v[162:165], v186 offset:8192
	v_mfma_f32_16x16x32_bf16 v[20:23], v[166:169], v[216:219], v[20:23]
	v_mfma_f32_16x16x32_bf16 v[24:27], v[166:169], v[240:243], v[24:27]
	v_mfma_f32_16x16x32_bf16 v[28:31], v[166:169], v[244:247], v[28:31]
	s_waitcnt lgkmcnt(2)
	v_mfma_f32_16x16x32_bf16 v[32:35], v[170:173], v[212:215], v[32:35]
	ds_read_b128 v[166:169], v186 offset:10240
	v_mfma_f32_16x16x32_bf16 v[36:39], v[170:173], v[216:219], v[36:39]
	v_mfma_f32_16x16x32_bf16 v[40:43], v[170:173], v[240:243], v[40:43]
	v_mfma_f32_16x16x32_bf16 v[44:47], v[170:173], v[244:247], v[44:47]
	s_waitcnt lgkmcnt(2)
	v_mfma_f32_16x16x32_bf16 v[48:51], v[174:177], v[212:215], v[48:51]
	ds_read_b128 v[170:173], v186 offset:12288
	v_mfma_f32_16x16x32_bf16 v[52:55], v[174:177], v[216:219], v[52:55]
	v_mfma_f32_16x16x32_bf16 v[56:59], v[174:177], v[240:243], v[56:59]
	v_mfma_f32_16x16x32_bf16 v[60:63], v[174:177], v[244:247], v[60:63]
	s_waitcnt lgkmcnt(2)
	v_mfma_f32_16x16x32_bf16 v[64:67], v[162:165], v[212:215], v[64:67]
	ds_read_b128 v[174:177], v186 offset:14336
	v_mfma_f32_16x16x32_bf16 v[68:71], v[162:165], v[216:219], v[68:71]
	v_mfma_f32_16x16x32_bf16 v[72:75], v[162:165], v[240:243], v[72:75]
	v_mfma_f32_16x16x32_bf16 v[76:79], v[162:165], v[244:247], v[76:79]
	s_waitcnt lgkmcnt(2)
	v_mfma_f32_16x16x32_bf16 v[80:83], v[166:169], v[212:215], v[80:83]
	v_mfma_f32_16x16x32_bf16 v[84:87], v[166:169], v[216:219], v[84:87]
	v_mfma_f32_16x16x32_bf16 v[88:91], v[166:169], v[240:243], v[88:91]
	v_mfma_f32_16x16x32_bf16 v[92:95], v[166:169], v[244:247], v[92:95]
	s_waitcnt lgkmcnt(0)
	s_waitcnt vmcnt(0)
	s_barrier
	v_xor_b32_e32 v161, 0x10000, v161
	v_xor_b32_e32 v186, 0x10000, v186
	v_xor_b32_e32 v187, 0x10000, v187
	v_xor_b32_e32 v248, 0x10000, v248
	v_mfma_f32_16x16x32_bf16 v[96:99], v[170:173], v[212:215], v[96:99]
	ds_read_b128 v[162:165], v161
	ds_read_b128 v[166:169], v161 offset:2048
	s_mov_b32 m0, s44
	v_mfma_f32_16x16x32_bf16 v[100:103], v[170:173], v[216:219], v[100:103]
	global_load_lds_dwordx4 v136, s[40:41]
	v_mfma_f32_16x16x32_bf16 v[104:107], v[170:173], v[240:243], v[104:107]
	ds_read_b128 v[178:181], v187 offset:32768
	ds_read_b128 v[182:185], v187 offset:34816
	s_add_u32 m0, s44, 0x8000
	v_mfma_f32_16x16x32_bf16 v[108:111], v[170:173], v[244:247], v[108:111]
	global_load_lds_dwordx4 v138, s[42:43]
	v_mfma_f32_16x16x32_bf16 v[112:115], v[174:177], v[212:215], v[112:115]
	ds_read_b128 v[170:173], v161 offset:4096
	s_add_u32 m0, s44, 0x2000
	v_mfma_f32_16x16x32_bf16 v[116:119], v[174:177], v[216:219], v[116:119]
	global_load_lds_dwordx4 v140, s[40:41]
	ds_read_b128 v[196:199], v187 offset:36864
	ds_read_b128 v[200:203], v187 offset:38912
	v_mfma_f32_16x16x32_bf16 v[120:123], v[174:177], v[240:243], v[120:123]
	s_add_u32 m0, s44, 0xa000
	v_mfma_f32_16x16x32_bf16 v[124:127], v[174:177], v[244:247], v[124:127]
	global_load_lds_dwordx4 v142, s[42:43]
	s_waitcnt lgkmcnt(4)
	v_mfma_f32_16x16x32_bf16 v[0:3], v[162:165], v[178:181], v[0:3]
	ds_read_b128 v[174:177], v161 offset:6144
	s_waitcnt lgkmcnt(4)
	v_mfma_f32_16x16x32_bf16 v[4:7], v[162:165], v[182:185], v[4:7]
	ds_read_b128 v[212:215], v248 offset:32768
	s_waitcnt lgkmcnt(3)
	v_mfma_f32_16x16x32_bf16 v[8:11], v[162:165], v[196:199], v[8:11]
	s_waitcnt lgkmcnt(2)
	v_mfma_f32_16x16x32_bf16 v[12:15], v[162:165], v[200:203], v[12:15]
	v_mfma_f32_16x16x32_bf16 v[16:19], v[166:169], v[178:181], v[16:19]
	ds_read_b128 v[162:165], v161 offset:8192
	v_mfma_f32_16x16x32_bf16 v[20:23], v[166:169], v[182:185], v[20:23]
	ds_read_b128 v[216:219], v248 offset:34816
	v_mfma_f32_16x16x32_bf16 v[24:27], v[166:169], v[196:199], v[24:27]
	v_mfma_f32_16x16x32_bf16 v[28:31], v[166:169], v[200:203], v[28:31]
	v_mfma_f32_16x16x32_bf16 v[32:35], v[170:173], v[178:181], v[32:35]
	ds_read_b128 v[166:169], v161 offset:10240
	v_mfma_f32_16x16x32_bf16 v[36:39], v[170:173], v[182:185], v[36:39]
	ds_read_b128 v[240:243], v248 offset:36864
	v_mfma_f32_16x16x32_bf16 v[40:43], v[170:173], v[196:199], v[40:43]
	s_add_u32 m0, s44, 0x4000
	v_mfma_f32_16x16x32_bf16 v[44:47], v[170:173], v[200:203], v[44:47]
	global_load_lds_dwordx4 v144, s[40:41]
	s_waitcnt lgkmcnt(5)
	v_mfma_f32_16x16x32_bf16 v[48:51], v[174:177], v[178:181], v[48:51]
	ds_read_b128 v[170:173], v161 offset:12288
	v_mfma_f32_16x16x32_bf16 v[52:55], v[174:177], v[182:185], v[52:55]
	ds_read_b128 v[244:247], v248 offset:38912
	v_mfma_f32_16x16x32_bf16 v[56:59], v[174:177], v[196:199], v[56:59]
	s_add_u32 m0, s44, 0xc000
	v_mfma_f32_16x16x32_bf16 v[60:63], v[174:177], v[200:203], v[60:63]
	global_load_lds_dwordx4 v146, s[42:43]
	s_waitcnt lgkmcnt(5)
	v_mfma_f32_16x16x32_bf16 v[64:67], v[162:165], v[178:181], v[64:67]
	ds_read_b128 v[174:177], v161 offset:14336
	v_mfma_f32_16x16x32_bf16 v[68:71], v[162:165], v[182:185], v[68:71]
	v_mfma_f32_16x16x32_bf16 v[72:75], v[162:165], v[196:199], v[72:75]
	s_add_u32 m0, s44, 0x6000
	v_mfma_f32_16x16x32_bf16 v[76:79], v[162:165], v[200:203], v[76:79]
	global_load_lds_dwordx4 v148, s[40:41]
	s_waitcnt lgkmcnt(4)
	v_mfma_f32_16x16x32_bf16 v[80:83], v[166:169], v[178:181], v[80:83]
	ds_read_b128 v[162:165], v186
	v_mfma_f32_16x16x32_bf16 v[84:87], v[166:169], v[182:185], v[84:87]
	v_mfma_f32_16x16x32_bf16 v[88:91], v[166:169], v[196:199], v[88:91]
	s_add_u32 m0, s44, 0xe000
	v_mfma_f32_16x16x32_bf16 v[92:95], v[166:169], v[200:203], v[92:95]
	global_load_lds_dwordx4 v150, s[42:43]
	s_add_u32 s40, s40, 0x80
	s_addc_u32 s41, s41, 0
	s_add_u32 s42, s42, 0x80
	s_addc_u32 s43, s43, 0
	s_waitcnt lgkmcnt(3)
	v_mfma_f32_16x16x32_bf16 v[96:99], v[170:173], v[178:181], v[96:99]
	ds_read_b128 v[166:169], v186 offset:2048
	v_mfma_f32_16x16x32_bf16 v[100:103], v[170:173], v[182:185], v[100:103]
	v_mfma_f32_16x16x32_bf16 v[104:107], v[170:173], v[196:199], v[104:107]
	v_mfma_f32_16x16x32_bf16 v[108:111], v[170:173], v[200:203], v[108:111]
	s_waitcnt lgkmcnt(2)
	v_mfma_f32_16x16x32_bf16 v[112:115], v[174:177], v[178:181], v[112:115]
	ds_read_b128 v[170:173], v186 offset:4096
	v_mfma_f32_16x16x32_bf16 v[116:119], v[174:177], v[182:185], v[116:119]
	v_mfma_f32_16x16x32_bf16 v[120:123], v[174:177], v[196:199], v[120:123]
	v_mfma_f32_16x16x32_bf16 v[124:127], v[174:177], v[200:203], v[124:127]
	s_waitcnt lgkmcnt(2)
	v_mfma_f32_16x16x32_bf16 v[0:3], v[162:165], v[212:215], v[0:3]
	ds_read_b128 v[174:177], v186 offset:6144
	v_mfma_f32_16x16x32_bf16 v[4:7], v[162:165], v[216:219], v[4:7]
	v_mfma_f32_16x16x32_bf16 v[8:11], v[162:165], v[240:243], v[8:11]
	v_mfma_f32_16x16x32_bf16 v[12:15], v[162:165], v[244:247], v[12:15]
	s_waitcnt lgkmcnt(2)
	v_mfma_f32_16x16x32_bf16 v[16:19], v[166:169], v[212:215], v[16:19]
	ds_read_b128 v[162:165], v186 offset:8192
	v_mfma_f32_16x16x32_bf16 v[20:23], v[166:169], v[216:219], v[20:23]
	v_mfma_f32_16x16x32_bf16 v[24:27], v[166:169], v[240:243], v[24:27]
	v_mfma_f32_16x16x32_bf16 v[28:31], v[166:169], v[244:247], v[28:31]
	s_waitcnt lgkmcnt(2)
	v_mfma_f32_16x16x32_bf16 v[32:35], v[170:173], v[212:215], v[32:35]
	ds_read_b128 v[166:169], v186 offset:10240
	v_mfma_f32_16x16x32_bf16 v[36:39], v[170:173], v[216:219], v[36:39]
	v_mfma_f32_16x16x32_bf16 v[40:43], v[170:173], v[240:243], v[40:43]
	v_mfma_f32_16x16x32_bf16 v[44:47], v[170:173], v[244:247], v[44:47]
	s_waitcnt lgkmcnt(2)
	v_mfma_f32_16x16x32_bf16 v[48:51], v[174:177], v[212:215], v[48:51]
	ds_read_b128 v[170:173], v186 offset:12288
	v_mfma_f32_16x16x32_bf16 v[52:55], v[174:177], v[216:219], v[52:55]
	v_mfma_f32_16x16x32_bf16 v[56:59], v[174:177], v[240:243], v[56:59]
	v_mfma_f32_16x16x32_bf16 v[60:63], v[174:177], v[244:247], v[60:63]
	s_waitcnt lgkmcnt(2)
	v_mfma_f32_16x16x32_bf16 v[64:67], v[162:165], v[212:215], v[64:67]
	ds_read_b128 v[174:177], v186 offset:14336
	v_mfma_f32_16x16x32_bf16 v[68:71], v[162:165], v[216:219], v[68:71]
	v_mfma_f32_16x16x32_bf16 v[72:75], v[162:165], v[240:243], v[72:75]
	v_mfma_f32_16x16x32_bf16 v[76:79], v[162:165], v[244:247], v[76:79]
	s_waitcnt lgkmcnt(2)
	v_mfma_f32_16x16x32_bf16 v[80:83], v[166:169], v[212:215], v[80:83]
	v_mfma_f32_16x16x32_bf16 v[84:87], v[166:169], v[216:219], v[84:87]
	v_mfma_f32_16x16x32_bf16 v[88:91], v[166:169], v[240:243], v[88:91]
	v_mfma_f32_16x16x32_bf16 v[92:95], v[166:169], v[244:247], v[92:95]
	s_waitcnt lgkmcnt(0)
	s_waitcnt vmcnt(0)
	s_barrier
	v_xor_b32_e32 v161, 0x10000, v161
	v_xor_b32_e32 v186, 0x10000, v186
	v_xor_b32_e32 v187, 0x10000, v187
	v_xor_b32_e32 v248, 0x10000, v248
	v_mfma_f32_16x16x32_bf16 v[96:99], v[170:173], v[212:215], v[96:99]
	ds_read_b128 v[162:165], v161
	ds_read_b128 v[166:169], v161 offset:2048
	s_add_u32 m0, s44, 0x10000
	v_mfma_f32_16x16x32_bf16 v[100:103], v[170:173], v[216:219], v[100:103]
	global_load_lds_dwordx4 v136, s[40:41]
	v_mfma_f32_16x16x32_bf16 v[104:107], v[170:173], v[240:243], v[104:107]
	ds_read_b128 v[178:181], v187 offset:32768
	ds_read_b128 v[182:185], v187 offset:34816
	s_add_u32 m0, s44, 0x18000
	v_mfma_f32_16x16x32_bf16 v[108:111], v[170:173], v[244:247], v[108:111]
	global_load_lds_dwordx4 v138, s[42:43]
	v_mfma_f32_16x16x32_bf16 v[112:115], v[174:177], v[212:215], v[112:115]
	ds_read_b128 v[170:173], v161 offset:4096
	s_add_u32 m0, s44, 0x12000
	v_mfma_f32_16x16x32_bf16 v[116:119], v[174:177], v[216:219], v[116:119]
	global_load_lds_dwordx4 v140, s[40:41]
	ds_read_b128 v[196:199], v187 offset:36864
	ds_read_b128 v[200:203], v187 offset:38912
	v_mfma_f32_16x16x32_bf16 v[120:123], v[174:177], v[240:243], v[120:123]
	s_add_u32 m0, s44, 0x1a000
	v_mfma_f32_16x16x32_bf16 v[124:127], v[174:177], v[244:247], v[124:127]
	global_load_lds_dwordx4 v142, s[42:43]
	s_waitcnt lgkmcnt(4)
	v_mfma_f32_16x16x32_bf16 v[0:3], v[162:165], v[178:181], v[0:3]
	ds_read_b128 v[174:177], v161 offset:6144
	s_waitcnt lgkmcnt(4)
	v_mfma_f32_16x16x32_bf16 v[4:7], v[162:165], v[182:185], v[4:7]
	ds_read_b128 v[212:215], v248 offset:32768
	s_waitcnt lgkmcnt(3)
	v_mfma_f32_16x16x32_bf16 v[8:11], v[162:165], v[196:199], v[8:11]
	s_waitcnt lgkmcnt(2)
	v_mfma_f32_16x16x32_bf16 v[12:15], v[162:165], v[200:203], v[12:15]
	v_mfma_f32_16x16x32_bf16 v[16:19], v[166:169], v[178:181], v[16:19]
	ds_read_b128 v[162:165], v161 offset:8192
	v_mfma_f32_16x16x32_bf16 v[20:23], v[166:169], v[182:185], v[20:23]
	ds_read_b128 v[216:219], v248 offset:34816
	v_mfma_f32_16x16x32_bf16 v[24:27], v[166:169], v[196:199], v[24:27]
	v_mfma_f32_16x16x32_bf16 v[28:31], v[166:169], v[200:203], v[28:31]
	v_mfma_f32_16x16x32_bf16 v[32:35], v[170:173], v[178:181], v[32:35]
	ds_read_b128 v[166:169], v161 offset:10240
	v_mfma_f32_16x16x32_bf16 v[36:39], v[170:173], v[182:185], v[36:39]
	ds_read_b128 v[240:243], v248 offset:36864
	v_mfma_f32_16x16x32_bf16 v[40:43], v[170:173], v[196:199], v[40:43]
	s_add_u32 m0, s44, 0x14000
	v_mfma_f32_16x16x32_bf16 v[44:47], v[170:173], v[200:203], v[44:47]
	global_load_lds_dwordx4 v144, s[40:41]
	s_waitcnt lgkmcnt(5)
	v_mfma_f32_16x16x32_bf16 v[48:51], v[174:177], v[178:181], v[48:51]
	ds_read_b128 v[170:173], v161 offset:12288
	v_mfma_f32_16x16x32_bf16 v[52:55], v[174:177], v[182:185], v[52:55]
	ds_read_b128 v[244:247], v248 offset:38912
	v_mfma_f32_16x16x32_bf16 v[56:59], v[174:177], v[196:199], v[56:59]
	s_add_u32 m0, s44, 0x1c000
	v_mfma_f32_16x16x32_bf16 v[60:63], v[174:177], v[200:203], v[60:63]
	global_load_lds_dwordx4 v146, s[42:43]
	s_waitcnt lgkmcnt(5)
	v_mfma_f32_16x16x32_bf16 v[64:67], v[162:165], v[178:181], v[64:67]
	ds_read_b128 v[174:177], v161 offset:14336
	v_mfma_f32_16x16x32_bf16 v[68:71], v[162:165], v[182:185], v[68:71]
	v_mfma_f32_16x16x32_bf16 v[72:75], v[162:165], v[196:199], v[72:75]
	s_add_u32 m0, s44, 0x16000
	v_mfma_f32_16x16x32_bf16 v[76:79], v[162:165], v[200:203], v[76:79]
	global_load_lds_dwordx4 v148, s[40:41]
	s_waitcnt lgkmcnt(4)
	v_mfma_f32_16x16x32_bf16 v[80:83], v[166:169], v[178:181], v[80:83]
	ds_read_b128 v[162:165], v186
	v_mfma_f32_16x16x32_bf16 v[84:87], v[166:169], v[182:185], v[84:87]
	v_mfma_f32_16x16x32_bf16 v[88:91], v[166:169], v[196:199], v[88:91]
	s_add_u32 m0, s44, 0x1e000
	v_mfma_f32_16x16x32_bf16 v[92:95], v[166:169], v[200:203], v[92:95]
	global_load_lds_dwordx4 v150, s[42:43]
	s_add_u32 s40, s40, 0x80
	s_addc_u32 s41, s41, 0
	s_add_u32 s42, s42, 0x80
	s_addc_u32 s43, s43, 0
	s_waitcnt lgkmcnt(3)
	v_mfma_f32_16x16x32_bf16 v[96:99], v[170:173], v[178:181], v[96:99]
	ds_read_b128 v[166:169], v186 offset:2048
	v_mfma_f32_16x16x32_bf16 v[100:103], v[170:173], v[182:185], v[100:103]
	v_mfma_f32_16x16x32_bf16 v[104:107], v[170:173], v[196:199], v[104:107]
	v_mfma_f32_16x16x32_bf16 v[108:111], v[170:173], v[200:203], v[108:111]
	s_waitcnt lgkmcnt(2)
	v_mfma_f32_16x16x32_bf16 v[112:115], v[174:177], v[178:181], v[112:115]
	ds_read_b128 v[170:173], v186 offset:4096
	v_mfma_f32_16x16x32_bf16 v[116:119], v[174:177], v[182:185], v[116:119]
	v_mfma_f32_16x16x32_bf16 v[120:123], v[174:177], v[196:199], v[120:123]
	v_mfma_f32_16x16x32_bf16 v[124:127], v[174:177], v[200:203], v[124:127]
	s_waitcnt lgkmcnt(2)
	v_mfma_f32_16x16x32_bf16 v[0:3], v[162:165], v[212:215], v[0:3]
	ds_read_b128 v[174:177], v186 offset:6144
	v_mfma_f32_16x16x32_bf16 v[4:7], v[162:165], v[216:219], v[4:7]
	v_mfma_f32_16x16x32_bf16 v[8:11], v[162:165], v[240:243], v[8:11]
	v_mfma_f32_16x16x32_bf16 v[12:15], v[162:165], v[244:247], v[12:15]
	s_waitcnt lgkmcnt(2)
	v_mfma_f32_16x16x32_bf16 v[16:19], v[166:169], v[212:215], v[16:19]
	ds_read_b128 v[162:165], v186 offset:8192
	v_mfma_f32_16x16x32_bf16 v[20:23], v[166:169], v[216:219], v[20:23]
	v_mfma_f32_16x16x32_bf16 v[24:27], v[166:169], v[240:243], v[24:27]
	v_mfma_f32_16x16x32_bf16 v[28:31], v[166:169], v[244:247], v[28:31]
	s_waitcnt lgkmcnt(2)
	v_mfma_f32_16x16x32_bf16 v[32:35], v[170:173], v[212:215], v[32:35]
	ds_read_b128 v[166:169], v186 offset:10240
	v_mfma_f32_16x16x32_bf16 v[36:39], v[170:173], v[216:219], v[36:39]
	v_mfma_f32_16x16x32_bf16 v[40:43], v[170:173], v[240:243], v[40:43]
	v_mfma_f32_16x16x32_bf16 v[44:47], v[170:173], v[244:247], v[44:47]
	s_waitcnt lgkmcnt(2)
	v_mfma_f32_16x16x32_bf16 v[48:51], v[174:177], v[212:215], v[48:51]
	ds_read_b128 v[170:173], v186 offset:12288
	v_mfma_f32_16x16x32_bf16 v[52:55], v[174:177], v[216:219], v[52:55]
	v_mfma_f32_16x16x32_bf16 v[56:59], v[174:177], v[240:243], v[56:59]
	v_mfma_f32_16x16x32_bf16 v[60:63], v[174:177], v[244:247], v[60:63]
	s_waitcnt lgkmcnt(2)
	v_mfma_f32_16x16x32_bf16 v[64:67], v[162:165], v[212:215], v[64:67]
	ds_read_b128 v[174:177], v186 offset:14336
	v_mfma_f32_16x16x32_bf16 v[68:71], v[162:165], v[216:219], v[68:71]
	v_mfma_f32_16x16x32_bf16 v[72:75], v[162:165], v[240:243], v[72:75]
	v_mfma_f32_16x16x32_bf16 v[76:79], v[162:165], v[244:247], v[76:79]
	s_waitcnt lgkmcnt(2)
	v_mfma_f32_16x16x32_bf16 v[80:83], v[166:169], v[212:215], v[80:83]
	v_mfma_f32_16x16x32_bf16 v[84:87], v[166:169], v[216:219], v[84:87]
	v_mfma_f32_16x16x32_bf16 v[88:91], v[166:169], v[240:243], v[88:91]
	v_mfma_f32_16x16x32_bf16 v[92:95], v[166:169], v[244:247], v[92:95]
	s_waitcnt lgkmcnt(0)
	s_waitcnt vmcnt(0)
	s_barrier
	v_xor_b32_e32 v161, 0x10000, v161
	v_xor_b32_e32 v186, 0x10000, v186
	v_xor_b32_e32 v187, 0x10000, v187
	v_xor_b32_e32 v248, 0x10000, v248
	v_mfma_f32_16x16x32_bf16 v[96:99], v[170:173], v[212:215], v[96:99]
	ds_read_b128 v[162:165], v161
	ds_read_b128 v[166:169], v161 offset:2048
	s_mov_b32 m0, s44
	v_mfma_f32_16x16x32_bf16 v[100:103], v[170:173], v[216:219], v[100:103]
	global_load_lds_dwordx4 v136, s[40:41]
	v_mfma_f32_16x16x32_bf16 v[104:107], v[170:173], v[240:243], v[104:107]
	ds_read_b128 v[178:181], v187 offset:32768
	ds_read_b128 v[182:185], v187 offset:34816
	s_add_u32 m0, s44, 0x8000
	v_mfma_f32_16x16x32_bf16 v[108:111], v[170:173], v[244:247], v[108:111]
	global_load_lds_dwordx4 v138, s[42:43]
	v_mfma_f32_16x16x32_bf16 v[112:115], v[174:177], v[212:215], v[112:115]
	ds_read_b128 v[170:173], v161 offset:4096
	s_add_u32 m0, s44, 0x2000
	v_mfma_f32_16x16x32_bf16 v[116:119], v[174:177], v[216:219], v[116:119]
	global_load_lds_dwordx4 v140, s[40:41]
	ds_read_b128 v[196:199], v187 offset:36864
	ds_read_b128 v[200:203], v187 offset:38912
	v_mfma_f32_16x16x32_bf16 v[120:123], v[174:177], v[240:243], v[120:123]
	s_add_u32 m0, s44, 0xa000
	v_mfma_f32_16x16x32_bf16 v[124:127], v[174:177], v[244:247], v[124:127]
	global_load_lds_dwordx4 v142, s[42:43]
	s_waitcnt lgkmcnt(4)
	v_mfma_f32_16x16x32_bf16 v[0:3], v[162:165], v[178:181], v[0:3]
	ds_read_b128 v[174:177], v161 offset:6144
	s_waitcnt lgkmcnt(4)
	v_mfma_f32_16x16x32_bf16 v[4:7], v[162:165], v[182:185], v[4:7]
	ds_read_b128 v[212:215], v248 offset:32768
	s_waitcnt lgkmcnt(3)
	v_mfma_f32_16x16x32_bf16 v[8:11], v[162:165], v[196:199], v[8:11]
	s_waitcnt lgkmcnt(2)
	v_mfma_f32_16x16x32_bf16 v[12:15], v[162:165], v[200:203], v[12:15]
	v_mfma_f32_16x16x32_bf16 v[16:19], v[166:169], v[178:181], v[16:19]
	ds_read_b128 v[162:165], v161 offset:8192
	v_mfma_f32_16x16x32_bf16 v[20:23], v[166:169], v[182:185], v[20:23]
	ds_read_b128 v[216:219], v248 offset:34816
	v_mfma_f32_16x16x32_bf16 v[24:27], v[166:169], v[196:199], v[24:27]
	v_mfma_f32_16x16x32_bf16 v[28:31], v[166:169], v[200:203], v[28:31]
	v_mfma_f32_16x16x32_bf16 v[32:35], v[170:173], v[178:181], v[32:35]
	ds_read_b128 v[166:169], v161 offset:10240
	v_mfma_f32_16x16x32_bf16 v[36:39], v[170:173], v[182:185], v[36:39]
	ds_read_b128 v[240:243], v248 offset:36864
	v_mfma_f32_16x16x32_bf16 v[40:43], v[170:173], v[196:199], v[40:43]
	s_add_u32 m0, s44, 0x4000
	v_mfma_f32_16x16x32_bf16 v[44:47], v[170:173], v[200:203], v[44:47]
	global_load_lds_dwordx4 v144, s[40:41]
	s_waitcnt lgkmcnt(5)
	v_mfma_f32_16x16x32_bf16 v[48:51], v[174:177], v[178:181], v[48:51]
	ds_read_b128 v[170:173], v161 offset:12288
	v_mfma_f32_16x16x32_bf16 v[52:55], v[174:177], v[182:185], v[52:55]
	ds_read_b128 v[244:247], v248 offset:38912
	v_mfma_f32_16x16x32_bf16 v[56:59], v[174:177], v[196:199], v[56:59]
	s_add_u32 m0, s44, 0xc000
	v_mfma_f32_16x16x32_bf16 v[60:63], v[174:177], v[200:203], v[60:63]
	global_load_lds_dwordx4 v146, s[42:43]
	s_waitcnt lgkmcnt(5)
	v_mfma_f32_16x16x32_bf16 v[64:67], v[162:165], v[178:181], v[64:67]
	ds_read_b128 v[174:177], v161 offset:14336
	v_mfma_f32_16x16x32_bf16 v[68:71], v[162:165], v[182:185], v[68:71]
	v_mfma_f32_16x16x32_bf16 v[72:75], v[162:165], v[196:199], v[72:75]
	s_add_u32 m0, s44, 0x6000
	v_mfma_f32_16x16x32_bf16 v[76:79], v[162:165], v[200:203], v[76:79]
	global_load_lds_dwordx4 v148, s[40:41]
	s_waitcnt lgkmcnt(4)
	v_mfma_f32_16x16x32_bf16 v[80:83], v[166:169], v[178:181], v[80:83]
	ds_read_b128 v[162:165], v186
	v_mfma_f32_16x16x32_bf16 v[84:87], v[166:169], v[182:185], v[84:87]
	v_mfma_f32_16x16x32_bf16 v[88:91], v[166:169], v[196:199], v[88:91]
	s_add_u32 m0, s44, 0xe000
	v_mfma_f32_16x16x32_bf16 v[92:95], v[166:169], v[200:203], v[92:95]
	global_load_lds_dwordx4 v150, s[42:43]
	s_add_u32 s40, s40, 0x80
	s_addc_u32 s41, s41, 0
	s_add_u32 s42, s42, 0x80
	s_addc_u32 s43, s43, 0
	s_waitcnt lgkmcnt(3)
	v_mfma_f32_16x16x32_bf16 v[96:99], v[170:173], v[178:181], v[96:99]
	ds_read_b128 v[166:169], v186 offset:2048
	v_mfma_f32_16x16x32_bf16 v[100:103], v[170:173], v[182:185], v[100:103]
	v_mfma_f32_16x16x32_bf16 v[104:107], v[170:173], v[196:199], v[104:107]
	v_mfma_f32_16x16x32_bf16 v[108:111], v[170:173], v[200:203], v[108:111]
	s_waitcnt lgkmcnt(2)
	v_mfma_f32_16x16x32_bf16 v[112:115], v[174:177], v[178:181], v[112:115]
	ds_read_b128 v[170:173], v186 offset:4096
	v_mfma_f32_16x16x32_bf16 v[116:119], v[174:177], v[182:185], v[116:119]
	v_mfma_f32_16x16x32_bf16 v[120:123], v[174:177], v[196:199], v[120:123]
	v_mfma_f32_16x16x32_bf16 v[124:127], v[174:177], v[200:203], v[124:127]
	s_waitcnt lgkmcnt(2)
	v_mfma_f32_16x16x32_bf16 v[0:3], v[162:165], v[212:215], v[0:3]
	ds_read_b128 v[174:177], v186 offset:6144
	v_mfma_f32_16x16x32_bf16 v[4:7], v[162:165], v[216:219], v[4:7]
	v_mfma_f32_16x16x32_bf16 v[8:11], v[162:165], v[240:243], v[8:11]
	v_mfma_f32_16x16x32_bf16 v[12:15], v[162:165], v[244:247], v[12:15]
	s_waitcnt lgkmcnt(2)
	v_mfma_f32_16x16x32_bf16 v[16:19], v[166:169], v[212:215], v[16:19]
	ds_read_b128 v[162:165], v186 offset:8192
	v_mfma_f32_16x16x32_bf16 v[20:23], v[166:169], v[216:219], v[20:23]
	v_mfma_f32_16x16x32_bf16 v[24:27], v[166:169], v[240:243], v[24:27]
	v_mfma_f32_16x16x32_bf16 v[28:31], v[166:169], v[244:247], v[28:31]
	s_waitcnt lgkmcnt(2)
	v_mfma_f32_16x16x32_bf16 v[32:35], v[170:173], v[212:215], v[32:35]
	ds_read_b128 v[166:169], v186 offset:10240
	v_mfma_f32_16x16x32_bf16 v[36:39], v[170:173], v[216:219], v[36:39]
	v_mfma_f32_16x16x32_bf16 v[40:43], v[170:173], v[240:243], v[40:43]
	v_mfma_f32_16x16x32_bf16 v[44:47], v[170:173], v[244:247], v[44:47]
	s_waitcnt lgkmcnt(2)
	v_mfma_f32_16x16x32_bf16 v[48:51], v[174:177], v[212:215], v[48:51]
	ds_read_b128 v[170:173], v186 offset:12288
	v_mfma_f32_16x16x32_bf16 v[52:55], v[174:177], v[216:219], v[52:55]
	v_mfma_f32_16x16x32_bf16 v[56:59], v[174:177], v[240:243], v[56:59]
	v_mfma_f32_16x16x32_bf16 v[60:63], v[174:177], v[244:247], v[60:63]
	s_waitcnt lgkmcnt(2)
	v_mfma_f32_16x16x32_bf16 v[64:67], v[162:165], v[212:215], v[64:67]
	ds_read_b128 v[174:177], v186 offset:14336
	v_mfma_f32_16x16x32_bf16 v[68:71], v[162:165], v[216:219], v[68:71]
	v_mfma_f32_16x16x32_bf16 v[72:75], v[162:165], v[240:243], v[72:75]
	v_mfma_f32_16x16x32_bf16 v[76:79], v[162:165], v[244:247], v[76:79]
	s_waitcnt lgkmcnt(2)
	v_mfma_f32_16x16x32_bf16 v[80:83], v[166:169], v[212:215], v[80:83]
	v_mfma_f32_16x16x32_bf16 v[84:87], v[166:169], v[216:219], v[84:87]
	v_mfma_f32_16x16x32_bf16 v[88:91], v[166:169], v[240:243], v[88:91]
	v_mfma_f32_16x16x32_bf16 v[92:95], v[166:169], v[244:247], v[92:95]
	s_waitcnt lgkmcnt(0)
	s_waitcnt vmcnt(0)
	s_barrier
	v_xor_b32_e32 v161, 0x10000, v161
	v_xor_b32_e32 v186, 0x10000, v186
	v_xor_b32_e32 v187, 0x10000, v187
	v_xor_b32_e32 v248, 0x10000, v248
	v_mfma_f32_16x16x32_bf16 v[96:99], v[170:173], v[212:215], v[96:99]
	ds_read_b128 v[162:165], v161
	ds_read_b128 v[166:169], v161 offset:2048
	s_add_u32 m0, s44, 0x10000
	v_mfma_f32_16x16x32_bf16 v[100:103], v[170:173], v[216:219], v[100:103]
	global_load_lds_dwordx4 v136, s[40:41]
	v_mfma_f32_16x16x32_bf16 v[104:107], v[170:173], v[240:243], v[104:107]
	ds_read_b128 v[178:181], v187 offset:32768
	ds_read_b128 v[182:185], v187 offset:34816
	s_add_u32 m0, s44, 0x18000
	v_mfma_f32_16x16x32_bf16 v[108:111], v[170:173], v[244:247], v[108:111]
	global_load_lds_dwordx4 v138, s[42:43]
	v_mfma_f32_16x16x32_bf16 v[112:115], v[174:177], v[212:215], v[112:115]
	ds_read_b128 v[170:173], v161 offset:4096
	s_add_u32 m0, s44, 0x12000
	v_mfma_f32_16x16x32_bf16 v[116:119], v[174:177], v[216:219], v[116:119]
	global_load_lds_dwordx4 v140, s[40:41]
	ds_read_b128 v[196:199], v187 offset:36864
	ds_read_b128 v[200:203], v187 offset:38912
	v_mfma_f32_16x16x32_bf16 v[120:123], v[174:177], v[240:243], v[120:123]
	s_add_u32 m0, s44, 0x1a000
	v_mfma_f32_16x16x32_bf16 v[124:127], v[174:177], v[244:247], v[124:127]
	global_load_lds_dwordx4 v142, s[42:43]
	s_waitcnt lgkmcnt(4)
	v_mfma_f32_16x16x32_bf16 v[0:3], v[162:165], v[178:181], v[0:3]
	ds_read_b128 v[174:177], v161 offset:6144
	s_waitcnt lgkmcnt(4)
	v_mfma_f32_16x16x32_bf16 v[4:7], v[162:165], v[182:185], v[4:7]
	ds_read_b128 v[212:215], v248 offset:32768
	s_waitcnt lgkmcnt(3)
	v_mfma_f32_16x16x32_bf16 v[8:11], v[162:165], v[196:199], v[8:11]
	s_waitcnt lgkmcnt(2)
	v_mfma_f32_16x16x32_bf16 v[12:15], v[162:165], v[200:203], v[12:15]
	v_mfma_f32_16x16x32_bf16 v[16:19], v[166:169], v[178:181], v[16:19]
	ds_read_b128 v[162:165], v161 offset:8192
	v_mfma_f32_16x16x32_bf16 v[20:23], v[166:169], v[182:185], v[20:23]
	ds_read_b128 v[216:219], v248 offset:34816
	v_mfma_f32_16x16x32_bf16 v[24:27], v[166:169], v[196:199], v[24:27]
	v_mfma_f32_16x16x32_bf16 v[28:31], v[166:169], v[200:203], v[28:31]
	v_mfma_f32_16x16x32_bf16 v[32:35], v[170:173], v[178:181], v[32:35]
	ds_read_b128 v[166:169], v161 offset:10240
	v_mfma_f32_16x16x32_bf16 v[36:39], v[170:173], v[182:185], v[36:39]
	ds_read_b128 v[240:243], v248 offset:36864
	v_mfma_f32_16x16x32_bf16 v[40:43], v[170:173], v[196:199], v[40:43]
	s_add_u32 m0, s44, 0x14000
	v_mfma_f32_16x16x32_bf16 v[44:47], v[170:173], v[200:203], v[44:47]
	global_load_lds_dwordx4 v144, s[40:41]
	s_waitcnt lgkmcnt(5)
	v_mfma_f32_16x16x32_bf16 v[48:51], v[174:177], v[178:181], v[48:51]
	ds_read_b128 v[170:173], v161 offset:12288
	v_mfma_f32_16x16x32_bf16 v[52:55], v[174:177], v[182:185], v[52:55]
	ds_read_b128 v[244:247], v248 offset:38912
	v_mfma_f32_16x16x32_bf16 v[56:59], v[174:177], v[196:199], v[56:59]
	s_add_u32 m0, s44, 0x1c000
	v_mfma_f32_16x16x32_bf16 v[60:63], v[174:177], v[200:203], v[60:63]
	global_load_lds_dwordx4 v146, s[42:43]
	s_waitcnt lgkmcnt(5)
	v_mfma_f32_16x16x32_bf16 v[64:67], v[162:165], v[178:181], v[64:67]
	ds_read_b128 v[174:177], v161 offset:14336
	v_mfma_f32_16x16x32_bf16 v[68:71], v[162:165], v[182:185], v[68:71]
	v_mfma_f32_16x16x32_bf16 v[72:75], v[162:165], v[196:199], v[72:75]
	s_add_u32 m0, s44, 0x16000
	v_mfma_f32_16x16x32_bf16 v[76:79], v[162:165], v[200:203], v[76:79]
	global_load_lds_dwordx4 v148, s[40:41]
	s_waitcnt lgkmcnt(4)
	v_mfma_f32_16x16x32_bf16 v[80:83], v[166:169], v[178:181], v[80:83]
	ds_read_b128 v[162:165], v186
	v_mfma_f32_16x16x32_bf16 v[84:87], v[166:169], v[182:185], v[84:87]
	v_mfma_f32_16x16x32_bf16 v[88:91], v[166:169], v[196:199], v[88:91]
	s_add_u32 m0, s44, 0x1e000
	v_mfma_f32_16x16x32_bf16 v[92:95], v[166:169], v[200:203], v[92:95]
	global_load_lds_dwordx4 v150, s[42:43]
	s_add_u32 s40, s40, 0x80
	s_addc_u32 s41, s41, 0
	s_add_u32 s42, s42, 0x80
	s_addc_u32 s43, s43, 0
	s_waitcnt lgkmcnt(3)
	v_mfma_f32_16x16x32_bf16 v[96:99], v[170:173], v[178:181], v[96:99]
	ds_read_b128 v[166:169], v186 offset:2048
	v_mfma_f32_16x16x32_bf16 v[100:103], v[170:173], v[182:185], v[100:103]
	v_mfma_f32_16x16x32_bf16 v[104:107], v[170:173], v[196:199], v[104:107]
	v_mfma_f32_16x16x32_bf16 v[108:111], v[170:173], v[200:203], v[108:111]
	s_waitcnt lgkmcnt(2)
	v_mfma_f32_16x16x32_bf16 v[112:115], v[174:177], v[178:181], v[112:115]
	ds_read_b128 v[170:173], v186 offset:4096
	v_mfma_f32_16x16x32_bf16 v[116:119], v[174:177], v[182:185], v[116:119]
	v_mfma_f32_16x16x32_bf16 v[120:123], v[174:177], v[196:199], v[120:123]
	v_mfma_f32_16x16x32_bf16 v[124:127], v[174:177], v[200:203], v[124:127]
	s_waitcnt lgkmcnt(2)
	v_mfma_f32_16x16x32_bf16 v[0:3], v[162:165], v[212:215], v[0:3]
	ds_read_b128 v[174:177], v186 offset:6144
	v_mfma_f32_16x16x32_bf16 v[4:7], v[162:165], v[216:219], v[4:7]
	v_mfma_f32_16x16x32_bf16 v[8:11], v[162:165], v[240:243], v[8:11]
	v_mfma_f32_16x16x32_bf16 v[12:15], v[162:165], v[244:247], v[12:15]
	s_waitcnt lgkmcnt(2)
	v_mfma_f32_16x16x32_bf16 v[16:19], v[166:169], v[212:215], v[16:19]
	ds_read_b128 v[162:165], v186 offset:8192
	v_mfma_f32_16x16x32_bf16 v[20:23], v[166:169], v[216:219], v[20:23]
	v_mfma_f32_16x16x32_bf16 v[24:27], v[166:169], v[240:243], v[24:27]
	v_mfma_f32_16x16x32_bf16 v[28:31], v[166:169], v[244:247], v[28:31]
	s_waitcnt lgkmcnt(2)
	v_mfma_f32_16x16x32_bf16 v[32:35], v[170:173], v[212:215], v[32:35]
	ds_read_b128 v[166:169], v186 offset:10240
	v_mfma_f32_16x16x32_bf16 v[36:39], v[170:173], v[216:219], v[36:39]
	v_mfma_f32_16x16x32_bf16 v[40:43], v[170:173], v[240:243], v[40:43]
	v_mfma_f32_16x16x32_bf16 v[44:47], v[170:173], v[244:247], v[44:47]
	s_waitcnt lgkmcnt(2)
	v_mfma_f32_16x16x32_bf16 v[48:51], v[174:177], v[212:215], v[48:51]
	ds_read_b128 v[170:173], v186 offset:12288
	v_mfma_f32_16x16x32_bf16 v[52:55], v[174:177], v[216:219], v[52:55]
	v_mfma_f32_16x16x32_bf16 v[56:59], v[174:177], v[240:243], v[56:59]
	v_mfma_f32_16x16x32_bf16 v[60:63], v[174:177], v[244:247], v[60:63]
	s_waitcnt lgkmcnt(2)
	v_mfma_f32_16x16x32_bf16 v[64:67], v[162:165], v[212:215], v[64:67]
	ds_read_b128 v[174:177], v186 offset:14336
	v_mfma_f32_16x16x32_bf16 v[68:71], v[162:165], v[216:219], v[68:71]
	v_mfma_f32_16x16x32_bf16 v[72:75], v[162:165], v[240:243], v[72:75]
	v_mfma_f32_16x16x32_bf16 v[76:79], v[162:165], v[244:247], v[76:79]
	s_waitcnt lgkmcnt(2)
	v_mfma_f32_16x16x32_bf16 v[80:83], v[166:169], v[212:215], v[80:83]
	v_mfma_f32_16x16x32_bf16 v[84:87], v[166:169], v[216:219], v[84:87]
	v_mfma_f32_16x16x32_bf16 v[88:91], v[166:169], v[240:243], v[88:91]
	v_mfma_f32_16x16x32_bf16 v[92:95], v[166:169], v[244:247], v[92:95]
	s_waitcnt lgkmcnt(0)
	s_waitcnt vmcnt(0)
	s_barrier
	v_xor_b32_e32 v161, 0x10000, v161
	v_xor_b32_e32 v186, 0x10000, v186
	v_xor_b32_e32 v187, 0x10000, v187
	v_xor_b32_e32 v248, 0x10000, v248
	v_mfma_f32_16x16x32_bf16 v[96:99], v[170:173], v[212:215], v[96:99]
	ds_read_b128 v[162:165], v161
	ds_read_b128 v[166:169], v161 offset:2048
	v_mfma_f32_16x16x32_bf16 v[100:103], v[170:173], v[216:219], v[100:103]
	v_mfma_f32_16x16x32_bf16 v[104:107], v[170:173], v[240:243], v[104:107]
	ds_read_b128 v[178:181], v187 offset:32768
	ds_read_b128 v[182:185], v187 offset:34816
	v_mfma_f32_16x16x32_bf16 v[108:111], v[170:173], v[244:247], v[108:111]
	v_mfma_f32_16x16x32_bf16 v[112:115], v[174:177], v[212:215], v[112:115]
	ds_read_b128 v[170:173], v161 offset:4096
	v_mfma_f32_16x16x32_bf16 v[116:119], v[174:177], v[216:219], v[116:119]
	ds_read_b128 v[196:199], v187 offset:36864
	ds_read_b128 v[200:203], v187 offset:38912
	v_mfma_f32_16x16x32_bf16 v[120:123], v[174:177], v[240:243], v[120:123]
	v_mfma_f32_16x16x32_bf16 v[124:127], v[174:177], v[244:247], v[124:127]
	s_waitcnt lgkmcnt(4)
	v_mfma_f32_16x16x32_bf16 v[0:3], v[162:165], v[178:181], v[0:3]
	ds_read_b128 v[174:177], v161 offset:6144
	s_waitcnt lgkmcnt(4)
	v_mfma_f32_16x16x32_bf16 v[4:7], v[162:165], v[182:185], v[4:7]
	ds_read_b128 v[212:215], v248 offset:32768
	s_waitcnt lgkmcnt(3)
	v_mfma_f32_16x16x32_bf16 v[8:11], v[162:165], v[196:199], v[8:11]
	s_waitcnt lgkmcnt(2)
	v_mfma_f32_16x16x32_bf16 v[12:15], v[162:165], v[200:203], v[12:15]
	v_mfma_f32_16x16x32_bf16 v[16:19], v[166:169], v[178:181], v[16:19]
	ds_read_b128 v[162:165], v161 offset:8192
	v_mfma_f32_16x16x32_bf16 v[20:23], v[166:169], v[182:185], v[20:23]
	ds_read_b128 v[216:219], v248 offset:34816
	v_mfma_f32_16x16x32_bf16 v[24:27], v[166:169], v[196:199], v[24:27]
	v_mfma_f32_16x16x32_bf16 v[28:31], v[166:169], v[200:203], v[28:31]
	v_mfma_f32_16x16x32_bf16 v[32:35], v[170:173], v[178:181], v[32:35]
	ds_read_b128 v[166:169], v161 offset:10240
	v_mfma_f32_16x16x32_bf16 v[36:39], v[170:173], v[182:185], v[36:39]
	ds_read_b128 v[240:243], v248 offset:36864
	v_mfma_f32_16x16x32_bf16 v[40:43], v[170:173], v[196:199], v[40:43]
	v_mfma_f32_16x16x32_bf16 v[44:47], v[170:173], v[200:203], v[44:47]
	s_waitcnt lgkmcnt(5)
	v_mfma_f32_16x16x32_bf16 v[48:51], v[174:177], v[178:181], v[48:51]
	ds_read_b128 v[170:173], v161 offset:12288
	v_mfma_f32_16x16x32_bf16 v[52:55], v[174:177], v[182:185], v[52:55]
	ds_read_b128 v[244:247], v248 offset:38912
	v_mfma_f32_16x16x32_bf16 v[56:59], v[174:177], v[196:199], v[56:59]
	v_mfma_f32_16x16x32_bf16 v[60:63], v[174:177], v[200:203], v[60:63]
	s_waitcnt lgkmcnt(5)
	v_mfma_f32_16x16x32_bf16 v[64:67], v[162:165], v[178:181], v[64:67]
	ds_read_b128 v[174:177], v161 offset:14336
	v_mfma_f32_16x16x32_bf16 v[68:71], v[162:165], v[182:185], v[68:71]
	v_mfma_f32_16x16x32_bf16 v[72:75], v[162:165], v[196:199], v[72:75]
	v_mfma_f32_16x16x32_bf16 v[76:79], v[162:165], v[200:203], v[76:79]
	s_waitcnt lgkmcnt(4)
	v_mfma_f32_16x16x32_bf16 v[80:83], v[166:169], v[178:181], v[80:83]
	ds_read_b128 v[162:165], v186
	v_mfma_f32_16x16x32_bf16 v[84:87], v[166:169], v[182:185], v[84:87]
	v_mfma_f32_16x16x32_bf16 v[88:91], v[166:169], v[196:199], v[88:91]
	v_mfma_f32_16x16x32_bf16 v[92:95], v[166:169], v[200:203], v[92:95]
	s_waitcnt lgkmcnt(3)
	v_mfma_f32_16x16x32_bf16 v[96:99], v[170:173], v[178:181], v[96:99]
	ds_read_b128 v[166:169], v186 offset:2048
	v_mfma_f32_16x16x32_bf16 v[100:103], v[170:173], v[182:185], v[100:103]
	v_mfma_f32_16x16x32_bf16 v[104:107], v[170:173], v[196:199], v[104:107]
	v_mfma_f32_16x16x32_bf16 v[108:111], v[170:173], v[200:203], v[108:111]
	s_waitcnt lgkmcnt(2)
	v_mfma_f32_16x16x32_bf16 v[112:115], v[174:177], v[178:181], v[112:115]
	ds_read_b128 v[170:173], v186 offset:4096
	v_mfma_f32_16x16x32_bf16 v[116:119], v[174:177], v[182:185], v[116:119]
	v_mfma_f32_16x16x32_bf16 v[120:123], v[174:177], v[196:199], v[120:123]
	v_mfma_f32_16x16x32_bf16 v[124:127], v[174:177], v[200:203], v[124:127]
	s_waitcnt lgkmcnt(2)
	v_mfma_f32_16x16x32_bf16 v[0:3], v[162:165], v[212:215], v[0:3]
	ds_read_b128 v[174:177], v186 offset:6144
	v_mfma_f32_16x16x32_bf16 v[4:7], v[162:165], v[216:219], v[4:7]
	v_mfma_f32_16x16x32_bf16 v[8:11], v[162:165], v[240:243], v[8:11]
	v_mfma_f32_16x16x32_bf16 v[12:15], v[162:165], v[244:247], v[12:15]
	s_waitcnt lgkmcnt(2)
	v_mfma_f32_16x16x32_bf16 v[16:19], v[166:169], v[212:215], v[16:19]
	ds_read_b128 v[162:165], v186 offset:8192
	v_mfma_f32_16x16x32_bf16 v[20:23], v[166:169], v[216:219], v[20:23]
	v_mfma_f32_16x16x32_bf16 v[24:27], v[166:169], v[240:243], v[24:27]
	v_mfma_f32_16x16x32_bf16 v[28:31], v[166:169], v[244:247], v[28:31]
	s_waitcnt lgkmcnt(2)
	v_mfma_f32_16x16x32_bf16 v[32:35], v[170:173], v[212:215], v[32:35]
	ds_read_b128 v[166:169], v186 offset:10240
	v_mfma_f32_16x16x32_bf16 v[36:39], v[170:173], v[216:219], v[36:39]
	v_mfma_f32_16x16x32_bf16 v[40:43], v[170:173], v[240:243], v[40:43]
	v_mfma_f32_16x16x32_bf16 v[44:47], v[170:173], v[244:247], v[44:47]
	s_waitcnt lgkmcnt(2)
	v_mfma_f32_16x16x32_bf16 v[48:51], v[174:177], v[212:215], v[48:51]
	ds_read_b128 v[170:173], v186 offset:12288
	v_mfma_f32_16x16x32_bf16 v[52:55], v[174:177], v[216:219], v[52:55]
	v_mfma_f32_16x16x32_bf16 v[56:59], v[174:177], v[240:243], v[56:59]
	v_mfma_f32_16x16x32_bf16 v[60:63], v[174:177], v[244:247], v[60:63]
	s_waitcnt lgkmcnt(2)
	v_mfma_f32_16x16x32_bf16 v[64:67], v[162:165], v[212:215], v[64:67]
	ds_read_b128 v[174:177], v186 offset:14336
	v_mfma_f32_16x16x32_bf16 v[68:71], v[162:165], v[216:219], v[68:71]
	v_mfma_f32_16x16x32_bf16 v[72:75], v[162:165], v[240:243], v[72:75]
	v_mfma_f32_16x16x32_bf16 v[76:79], v[162:165], v[244:247], v[76:79]
	s_waitcnt lgkmcnt(2)
	v_mfma_f32_16x16x32_bf16 v[80:83], v[166:169], v[212:215], v[80:83]
	v_mfma_f32_16x16x32_bf16 v[84:87], v[166:169], v[216:219], v[84:87]
	v_mfma_f32_16x16x32_bf16 v[88:91], v[166:169], v[240:243], v[88:91]
	v_mfma_f32_16x16x32_bf16 v[92:95], v[166:169], v[244:247], v[92:95]
	s_waitcnt lgkmcnt(0)
	s_waitcnt vmcnt(0)
	s_barrier
	v_xor_b32_e32 v161, 0x10000, v161
	v_xor_b32_e32 v186, 0x10000, v186
	v_xor_b32_e32 v187, 0x10000, v187
	v_xor_b32_e32 v248, 0x10000, v248
	v_mfma_f32_16x16x32_bf16 v[96:99], v[170:173], v[212:215], v[96:99]
	v_mfma_f32_16x16x32_bf16 v[100:103], v[170:173], v[216:219], v[100:103]
	v_mfma_f32_16x16x32_bf16 v[104:107], v[170:173], v[240:243], v[104:107]
	v_mfma_f32_16x16x32_bf16 v[108:111], v[170:173], v[244:247], v[108:111]
	v_mfma_f32_16x16x32_bf16 v[112:115], v[174:177], v[212:215], v[112:115]
	v_mfma_f32_16x16x32_bf16 v[116:119], v[174:177], v[216:219], v[116:119]
	v_mfma_f32_16x16x32_bf16 v[120:123], v[174:177], v[240:243], v[120:123]
	v_mfma_f32_16x16x32_bf16 v[124:127], v[174:177], v[244:247], v[124:127]
	s_mov_b32 m0, s39
	s_mov_b32 s38, 0
	s_mov_b64 s[26:27], -1
	v_add_u32_e32 v136, s24, v154
	s_mov_b32 s24, 0xc000
	v_mul_lo_u32 v192, v160, s24
	s_lshl_b32 s24, s37, 8
	v_ashrrev_i32_e32 v137, 31, v136
	v_or_b32_e32 v133, s24, v130
	v_lshl_add_u64 v[134:135], s[0:1], 0, v[192:193]
	v_lshlrev_b32_e32 v140, 8, v159
	v_lshl_add_u64 v[136:137], v[136:137], 1, v[128:129]
	v_sub_u32_e32 v133, v133, v140
	v_lshl_add_u64 v[138:139], s[22:23], 0, v[192:193]
	v_sub_u32_e32 v144, s24, v140
	s_nop 7
	s_nop 3
	s_branch .LBB0_806

.LBB0_806:
	v_mov_b32_e32 v140, v195
	s_nop 0
	v_ashrrev_i32_e32 v141, 8, v140
	v_cmp_eq_u32_e32 vcc, s38, v141
	s_and_saveexec_b64 s[24:25], vcc
	s_cbranch_execz .LBB0_808
	v_bfe_i32 v141, v195, 7, 1
	v_and_b32_e32 v141, 0x10c00, v141
	v_and_b32_e32 v142, 0x4f, v195
	v_lshl_or_b32 v141, v142, 2, v141
	v_bfe_u32 v140, v195, 4, 2
	v_mul_u32_u24_e32 v140, 0x840, v140
	v_add_u32_e32 v140, v140, v141
	v_mov_b32_e32 v141, v140
	v_add_u32_e32 v142, 0x420, v140
	ds_write2_b32 v141, v0, v1 offset1:132
	ds_write2_b32 v142, v2, v3 offset1:132
	ds_write2_b32 v141, v4, v5 offset0:16 offset1:148
	ds_write2_b32 v142, v6, v7 offset0:16 offset1:148
	ds_write2_b32 v141, v8, v9 offset0:32 offset1:164
	ds_write2_b32 v142, v10, v11 offset0:32 offset1:164
	ds_write2_b32 v141, v12, v13 offset0:48 offset1:180
	ds_write2_b32 v142, v14, v15 offset0:48 offset1:180
	v_add_u32_e32 v141, 0x2100, v140
	v_add_u32_e32 v142, 0x2520, v140
	ds_write2_b32 v141, v16, v17 offset1:132
	ds_write2_b32 v142, v18, v19 offset1:132
	ds_write2_b32 v141, v20, v21 offset0:16 offset1:148
	ds_write2_b32 v142, v22, v23 offset0:16 offset1:148
	ds_write2_b32 v141, v24, v25 offset0:32 offset1:164
	ds_write2_b32 v142, v26, v27 offset0:32 offset1:164
	ds_write2_b32 v141, v28, v29 offset0:48 offset1:180
	ds_write2_b32 v142, v30, v31 offset0:48 offset1:180
	v_add_u32_e32 v141, 0x4200, v140
	v_add_u32_e32 v142, 0x4620, v140
	ds_write2_b32 v141, v32, v33 offset1:132
	ds_write2_b32 v142, v34, v35 offset1:132
	ds_write2_b32 v141, v36, v37 offset0:16 offset1:148
	ds_write2_b32 v142, v38, v39 offset0:16 offset1:148
	ds_write2_b32 v141, v40, v41 offset0:32 offset1:164
	ds_write2_b32 v142, v42, v43 offset0:32 offset1:164
	ds_write2_b32 v141, v44, v45 offset0:48 offset1:180
	ds_write2_b32 v142, v46, v47 offset0:48 offset1:180
	v_add_u32_e32 v141, 0x6300, v140
	v_add_u32_e32 v142, 0x6720, v140
	ds_write2_b32 v141, v48, v49 offset1:132
	ds_write2_b32 v142, v50, v51 offset1:132
	ds_write2_b32 v141, v52, v53 offset0:16 offset1:148
	ds_write2_b32 v142, v54, v55 offset0:16 offset1:148
	ds_write2_b32 v141, v56, v57 offset0:32 offset1:164
	ds_write2_b32 v142, v58, v59 offset0:32 offset1:164
	ds_write2_b32 v141, v60, v61 offset0:48 offset1:180
	ds_write2_b32 v142, v62, v63 offset0:48 offset1:180
	v_add_u32_e32 v141, 0x8400, v140
	v_add_u32_e32 v142, 0x8820, v140
	ds_write2_b32 v141, v64, v65 offset1:132
	ds_write2_b32 v142, v66, v67 offset1:132
	ds_write2_b32 v141, v68, v69 offset0:16 offset1:148
	ds_write2_b32 v142, v70, v71 offset0:16 offset1:148
	ds_write2_b32 v141, v72, v73 offset0:32 offset1:164
	ds_write2_b32 v142, v74, v75 offset0:32 offset1:164
	ds_write2_b32 v141, v76, v77 offset0:48 offset1:180
	ds_write2_b32 v142, v78, v79 offset0:48 offset1:180
	v_add_u32_e32 v141, 0xa500, v140
	v_add_u32_e32 v142, 0xa920, v140
	ds_write2_b32 v141, v80, v81 offset1:132
	ds_write2_b32 v142, v82, v83 offset1:132
	ds_write2_b32 v141, v84, v85 offset0:16 offset1:148
	ds_write2_b32 v142, v86, v87 offset0:16 offset1:148
	ds_write2_b32 v141, v88, v89 offset0:32 offset1:164
	ds_write2_b32 v142, v90, v91 offset0:32 offset1:164
	ds_write2_b32 v141, v92, v93 offset0:48 offset1:180
	ds_write2_b32 v142, v94, v95 offset0:48 offset1:180
	v_add_u32_e32 v141, 0xc600, v140
	v_add_u32_e32 v142, 0xca20, v140
	ds_write2_b32 v141, v96, v97 offset1:132
	ds_write2_b32 v142, v98, v99 offset1:132
	ds_write2_b32 v141, v100, v101 offset0:16 offset1:148
	ds_write2_b32 v142, v102, v103 offset0:16 offset1:148
	ds_write2_b32 v141, v104, v105 offset0:32 offset1:164
	ds_write2_b32 v142, v106, v107 offset0:32 offset1:164
	ds_write2_b32 v141, v108, v109 offset0:48 offset1:180
	ds_write2_b32 v142, v110, v111 offset0:48 offset1:180
	v_add_u32_e32 v141, 0xe700, v140
	v_add_u32_e32 v142, 0xeb20, v140
	ds_write2_b32 v141, v112, v113 offset1:132
	ds_write2_b32 v142, v114, v115 offset1:132
	ds_write2_b32 v141, v116, v117 offset0:16 offset1:148
	ds_write2_b32 v142, v118, v119 offset0:16 offset1:148
	ds_write2_b32 v141, v120, v121 offset0:32 offset1:164
	ds_write2_b32 v142, v122, v123 offset0:32 offset1:164
	ds_write2_b32 v141, v124, v125 offset0:48 offset1:180
	ds_write2_b32 v142, v126, v127 offset0:48 offset1:180
